# instruction selection: UP GEMM accumulators zeroed with 64 v_mov_b64 instead of 128 v_mov_b32 per unit; otherwise as v65
# speedup vs baseline: 1.0033x; 1.0033x over previous
.LBB0_691:
	s_ashr_i32 s43, s42, 31
	s_lshl_b64 s[44:45], s[42:43], 19
	s_add_u32 s44, s55, s44
	s_addc_u32 s45, s56, s45
	s_and_b64 s[48:49], s[38:39], exec
	s_cselect_b32 s43, s45, s41
	s_cselect_b32 s66, s44, s40
	s_ashr_i32 s19, s18, 31
	s_lshl_b64 s[48:49], s[18:19], 19
	s_add_u32 s48, s52, s48
	s_addc_u32 s49, s53, s49
	s_and_b64 s[50:51], s[38:39], exec
	s_cselect_b32 s19, s49, s21
	s_cselect_b32 s67, s48, s20
	s_add_u32 s68, s20, 0x100
	s_addc_u32 s69, s21, 0
	s_add_u32 s40, s40, 0x40080
	v_mov_b64_e32 v[0:1], 0
	s_addc_u32 s41, s41, 0
	s_mov_b32 s70, -2
	v_mov_b64_e32 v[2:3], 0
	v_mov_b64_e32 v[4:5], 0
	v_mov_b64_e32 v[6:7], 0
	v_mov_b64_e32 v[8:9], 0
	v_mov_b64_e32 v[10:11], 0
	v_mov_b64_e32 v[12:13], 0
	v_mov_b64_e32 v[14:15], 0
	v_mov_b64_e32 v[16:17], 0
	v_mov_b64_e32 v[18:19], 0
	v_mov_b64_e32 v[20:21], 0
	v_mov_b64_e32 v[22:23], 0
	v_mov_b64_e32 v[24:25], 0
	v_mov_b64_e32 v[26:27], 0
	v_mov_b64_e32 v[28:29], 0
	v_mov_b64_e32 v[30:31], 0
	v_mov_b64_e32 v[32:33], 0
	v_mov_b64_e32 v[34:35], 0
	v_mov_b64_e32 v[36:37], 0
	v_mov_b64_e32 v[38:39], 0
	v_mov_b64_e32 v[40:41], 0
	v_mov_b64_e32 v[42:43], 0
	v_mov_b64_e32 v[44:45], 0
	v_mov_b64_e32 v[46:47], 0
	v_mov_b64_e32 v[48:49], 0
	v_mov_b64_e32 v[50:51], 0
	v_mov_b64_e32 v[52:53], 0
	v_mov_b64_e32 v[54:55], 0
	v_mov_b64_e32 v[56:57], 0
	v_mov_b64_e32 v[58:59], 0
	v_mov_b64_e32 v[60:61], 0
	v_mov_b64_e32 v[62:63], 0
	v_mov_b64_e32 v[64:65], 0
	v_mov_b64_e32 v[66:67], 0
	v_mov_b64_e32 v[68:69], 0
	v_mov_b64_e32 v[70:71], 0
	v_mov_b64_e32 v[72:73], 0
	v_mov_b64_e32 v[74:75], 0
	v_mov_b64_e32 v[76:77], 0
	v_mov_b64_e32 v[78:79], 0
	v_mov_b64_e32 v[80:81], 0
	v_mov_b64_e32 v[82:83], 0
	v_mov_b64_e32 v[84:85], 0
	v_mov_b64_e32 v[86:87], 0
	v_mov_b64_e32 v[88:89], 0
	v_mov_b64_e32 v[90:91], 0
	v_mov_b64_e32 v[92:93], 0
	v_mov_b64_e32 v[94:95], 0
	v_mov_b64_e32 v[96:97], 0
	v_mov_b64_e32 v[98:99], 0
	v_mov_b64_e32 v[100:101], 0
	v_mov_b64_e32 v[102:103], 0
	v_mov_b64_e32 v[104:105], 0
	v_mov_b64_e32 v[106:107], 0
	v_mov_b64_e32 v[108:109], 0
	v_mov_b64_e32 v[110:111], 0
	v_mov_b64_e32 v[112:113], 0
	v_mov_b64_e32 v[114:115], 0
	v_mov_b64_e32 v[116:117], 0
	v_mov_b64_e32 v[118:119], 0
	v_mov_b64_e32 v[120:121], 0
	v_mov_b64_e32 v[122:123], 0
	v_mov_b64_e32 v[124:125], 0
	v_mov_b64_e32 v[126:127], 0
